# P2b unit loop software-pipelined too: conv weights hoisted out of the loop (grid%8==0 path, original loop kept as fallback), next unit's 12 loads in flight, LDS tile double-buffered
# baseline (speedup 1.0000x reference)
; #define LAS __attribute__((address_space(3)))
; DI void p2b_unit(const Frame& F, int unit, const bf16* HY, bf16* UT, const float* cw, const float* cb) {
;     const int tt = unit >> 3, cgp = unit & 7;
;     LAS unsigned char* T = F.lds;
;     { const int t0 = F.tid >> 3, cc = (F.tid & 7) * 8, c0 = cgp * 64 + cc;
;       u32x4 xa[2], xb[2], xc[2], va[2], vb[2], vc[2];
; #pragma unroll
;       for (int j = 0; j < 2; ++j) { const int tok = tt * 128 + t0 + 64 * j; bool hp, hn; tok_edges(tok, hp, hn);
;           conv3_load(HY, tok, 512 + c0, hp, hn, xa[j], xb[j], xc[j]); conv3_load(HY, tok, 1024 + c0, hp, hn, va[j], vb[j], vc[j]); }
;       ConvW W1, WV; conv3_w(W1, cw, cb, 512 + c0); conv3_w(WV, cw, cb, 1024 + c0);
; __global__ void __launch_bounds__(512, 2) hybrid_fwd(Args args) {
;     ...
;     DUP_BEGIN(2) if (IN(2)) { for (int u = F.bid; u < 2048; u += F.G) p2b_unit(F, u, HY, UT, args.in[5], args.in[6]); }
.LBB0_680:
	s_cmp_lt_i32 s84, 3
	s_cselect_b64 s[0:1], -1, 0
	s_add_u32 s60, s80, 0x6000000
	s_addc_u32 s61, s81, 0
	s_and_b64 s[4:5], s[0:1], s[2:3]
	s_cmpk_lt_i32 s33, 0x800
	s_cselect_b64 s[0:1], -1, 0
	v_writelane_b32 v246, s0, 32
	v_lshlrev_b32_e32 v152, 3, v150
	s_nop 0
	v_writelane_b32 v246, s1, 33
	s_and_b64 s[0:1], s[4:5], s[0:1]
	s_andn2_b64 vcc, exec, s[0:1]
	s_cbranch_vccnz .LBB0_699
	v_lshlrev_b32_e32 v0, 3, v150
	v_and_b32_e32 v105, 56, v0
	s_add_u32 s6, s74, 0x1800
	v_lshrrev_b32_e32 v104, 3, v150
	s_addc_u32 s7, s75, 0
	s_movk_i32 s0, 0x110
	v_lshlrev_b32_e32 v107, 1, v105
	s_add_u32 s8, s74, 0x3000
	v_lshl_add_u32 v0, v104, 1, 0
	v_mul_u32_u24_e32 v1, 0x110, v105
	v_mad_u32_u24 v106, v104, s0, 0
	v_or_b32_e32 v2, 0x80, v107
	s_addc_u32 s9, s75, 0
	s_lshl_b32 s12, s33, 6
	s_lshl_b32 s13, s89, 6
	v_mov_b32_e32 v101, 0
	s_movk_i32 s14, 0x4000
	v_mov_b32_e32 v108, 0xfff
	s_movk_i32 s15, 0xc00
	v_mov_b64_e32 v[102:103], s[80:81]
	v_mov_b32_e32 v109, 0x3fff
	s_movk_i32 s16, 0x3fc0
	v_add_u32_e32 v110, v0, v1
	s_movk_i32 s17, 0x7f80
	v_add_u32_e32 v111, v106, v2
	s_mov_b32 s18, s33
	s_and_b32 s0, s89, 7
	s_cmp_lg_u32 s0, 0
	s_cbranch_scc1 .LBB0_683
	v_add_u32_e32 v96, v106, v107
	s_and_b32 s20, s12, 0x1c0
	v_or_b32_e32 v112, s20, v105
	v_lshlrev_b32_e32 v113, 2, v112
	v_or_b32_e32 v114, 0x800, v113
	v_or_b32_e32 v115, 0x1000, v113
	global_load_dwordx4 v[170:173], v114, s[6:7]
	global_load_dwordx4 v[174:177], v114, s[6:7] offset:16
	global_load_dwordx4 v[202:205], v115, s[6:7]
	global_load_dwordx4 v[206:209], v115, s[6:7] offset:16
	global_load_dwordx4 v[178:181], v113, s[74:75] offset:2048
	global_load_dwordx4 v[182:185], v113, s[74:75] offset:2064
	global_load_dwordx4 v[210:213], v115, s[74:75]
	global_load_dwordx4 v[214:217], v115, s[74:75] offset:16
	global_load_dwordx4 v[186:189], v114, s[8:9]
	global_load_dwordx4 v[190:193], v114, s[8:9] offset:16
	global_load_dwordx4 v[218:221], v115, s[8:9]
	global_load_dwordx4 v[222:225], v115, s[8:9] offset:16
	global_load_dwordx4 v[194:197], v113, s[76:77] offset:2048
	global_load_dwordx4 v[198:201], v113, s[76:77] offset:2064
	global_load_dwordx4 v[226:229], v115, s[76:77]
	global_load_dwordx4 v[230:233], v115, s[76:77] offset:16
	s_ashr_i32 s19, s18, 3
	s_and_b32 s20, s12, 0x1c0
	s_lshl_b32 s2, s19, 7
	v_or_b32_e32 v112, s20, v105
	v_or_b32_e32 v113, s2, v104
	v_mad_i64_i32 v[114:115], s[0:1], v113, s15, v[102:103]
	v_lshlrev_b32_e32 v98, 1, v112
	v_mov_b32_e32 v99, 0
	v_lshl_add_u64 v[114:115], v[114:115], 0, v[98:99]
	global_load_dwordx4 v[0:3], v[114:115], off offset:1024
	global_load_dwordx4 v[12:15], v[114:115], off offset:2048
	v_bitop3_b32 v116, s2, v108, v104 bitop3:0xc8
	v_add_u32_e32 v117, 0xffffc000, v113
	v_cmp_gt_i32_e32 vcc, s14, v113
	v_mov_b32_e32 v4, 0
	v_mov_b32_e32 v5, 0
	v_mov_b32_e32 v6, 0
	v_mov_b32_e32 v7, 0
	v_mov_b32_e32 v16, 0
	v_mov_b32_e32 v17, 0
	v_mov_b32_e32 v18, 0
	v_mov_b32_e32 v19, 0
	v_mov_b32_e32 v8, 0
	v_mov_b32_e32 v9, 0
	v_mov_b32_e32 v10, 0
	v_mov_b32_e32 v11, 0
	v_mov_b32_e32 v20, 0
	v_mov_b32_e32 v21, 0
	v_mov_b32_e32 v22, 0
	v_mov_b32_e32 v23, 0
	v_cndmask_b32_e32 v116, v117, v116, vcc
	v_cmp_ne_u32_e64 s[0:1], 0, v116
	v_cndmask_b32_e32 v117, v109, v108, vcc
	v_cmp_lt_u32_e64 s[2:3], v116, v117
	v_add_co_u32_e32 v118, vcc, 0x1000, v114
	s_nop 1
	v_addc_co_u32_e32 v119, vcc, 0, v115, vcc
	s_and_saveexec_b64 s[10:11], s[0:1]
	global_load_dwordx4 v[4:7], v[114:115], off offset:-2048
	global_load_dwordx4 v[16:19], v[114:115], off offset:-1024
	s_or_b64 exec, exec, s[10:11]
	s_and_saveexec_b64 s[10:11], s[2:3]
	global_load_dwordx4 v[8:11], v[118:119], off
	global_load_dwordx4 v[20:23], v[118:119], off offset:1024
	s_or_b64 exec, exec, s[10:11]
	s_lshl_b32 s2, s19, 7
	v_add_u32_e32 v120, 64, v113
	v_mad_i64_i32 v[114:115], s[0:1], v120, s15, v[102:103]
	v_lshl_add_u64 v[114:115], v[114:115], 0, v[98:99]
	global_load_dwordx4 v[24:27], v[114:115], off offset:1024
	global_load_dwordx4 v[36:39], v[114:115], off offset:2048
	v_and_b32_e32 v116, 0xfff, v120
	v_add_u32_e32 v117, 0xffffc040, v113
	v_cmp_gt_i32_e32 vcc, s16, v113
	v_mov_b32_e32 v28, 0
	v_mov_b32_e32 v29, 0
	v_mov_b32_e32 v30, 0
	v_mov_b32_e32 v31, 0
	v_mov_b32_e32 v40, 0
	v_mov_b32_e32 v41, 0
	v_mov_b32_e32 v42, 0
	v_mov_b32_e32 v43, 0
	v_mov_b32_e32 v32, 0
	v_mov_b32_e32 v33, 0
	v_mov_b32_e32 v34, 0
	v_mov_b32_e32 v35, 0
	v_mov_b32_e32 v44, 0
	v_mov_b32_e32 v45, 0
	v_mov_b32_e32 v46, 0
	v_mov_b32_e32 v47, 0
	v_cndmask_b32_e32 v116, v117, v116, vcc
	v_cmp_ne_u32_e64 s[0:1], 0, v116
	v_cndmask_b32_e32 v117, v109, v108, vcc
	v_cmp_lt_u32_e64 s[2:3], v116, v117
	v_add_co_u32_e32 v118, vcc, 0x1000, v114
	s_nop 1
	v_addc_co_u32_e32 v119, vcc, 0, v115, vcc
	s_and_saveexec_b64 s[10:11], s[0:1]
	global_load_dwordx4 v[28:31], v[114:115], off offset:-2048
	global_load_dwordx4 v[40:43], v[114:115], off offset:-1024
	s_or_b64 exec, exec, s[10:11]
	s_and_saveexec_b64 s[10:11], s[2:3]
	global_load_dwordx4 v[32:35], v[118:119], off
	global_load_dwordx4 v[44:47], v[118:119], off offset:1024
	s_or_b64 exec, exec, s[10:11]
	v_add_u32_e32 v116, s20, v104
	v_lshlrev_b32_e32 v120, 16, v116
	v_mov_b32_e32 v121, 0
	v_add_lshl_u32 v117, v116, s19, 7
	v_and_or_b32 v117, v117, s17, v105
	v_lshl_add_u64 v[120:121], s[60:61], 0, v[120:121]
	v_lshlrev_b32_e32 v122, 1, v117
	v_mov_b32_e32 v123, 0
	v_lshl_add_u64 v[234:235], v[120:121], 0, v[122:123]
; #define LAS __attribute__((address_space(3)))
; DI bf16 f2bf(float f) { return (bf16)(pk2(f, 0.f) & 0xffffu); }
; DI void p2b_unit(const Frame& F, int unit, const bf16* HY, bf16* UT, const float* cw, const float* cb) {
;     ...
;     { const int t0 = F.tid >> 3, cc = (F.tid & 7) * 8, c0 = cgp * 64 + cc;
;       u32x4 xa[2], xb[2], xc[2], va[2], vb[2], vc[2];
; #pragma unroll
;       for (int j = 0; j < 2; ++j) { const int tok = tt * 128 + t0 + 64 * j; bool hp, hn; tok_edges(tok, hp, hn);
;           conv3_load(HY, tok, 512 + c0, hp, hn, xa[j], xb[j], xc[j]); conv3_load(HY, tok, 1024 + c0, hp, hn, va[j], vb[j], vc[j]); }
;       ConvW W1, WV; conv3_w(W1, cw, cb, 512 + c0); conv3_w(WV, cw, cb, 1024 + c0);
; #pragma unroll
;       for (int j = 0; j < 2; ++j) { float x1[8], hv[8]; conv3_do(W1, xa[j], xb[j], xc[j], x1); conv3_do(WV, va[j], vb[j], vc[j], hv);
; #pragma unroll
;           for (int e = 0; e < 8; ++e) *(LAS bf16*)(T + (cc + e) * TR_ROW + (t0 + 64 * j) * 2) = f2bf(x1[e] * hv[e]); } }
.Lp2b_loop:
	s_add_i32 s21, s18, s89
	s_add_i32 s22, s12, s13
	s_cmpk_lt_i32 s21, 0x800
	s_cbranch_scc0 .Lp2b_lastA
	s_ashr_i32 s19, s21, 3
	s_and_b32 s20, s22, 0x1c0
	s_lshl_b32 s2, s19, 7
	v_or_b32_e32 v112, s20, v105
	v_or_b32_e32 v113, s2, v104
	v_mad_i64_i32 v[114:115], s[0:1], v113, s15, v[102:103]
	v_lshlrev_b32_e32 v98, 1, v112
	v_mov_b32_e32 v99, 0
	v_lshl_add_u64 v[114:115], v[114:115], 0, v[98:99]
	global_load_dwordx4 v[48:51], v[114:115], off offset:1024
	global_load_dwordx4 v[60:63], v[114:115], off offset:2048
	v_bitop3_b32 v116, s2, v108, v104 bitop3:0xc8
	v_add_u32_e32 v117, 0xffffc000, v113
	v_cmp_gt_i32_e32 vcc, s14, v113
	v_mov_b32_e32 v52, 0
	v_mov_b32_e32 v53, 0
	v_mov_b32_e32 v54, 0
	v_mov_b32_e32 v55, 0
	v_mov_b32_e32 v64, 0
	v_mov_b32_e32 v65, 0
	v_mov_b32_e32 v66, 0
	v_mov_b32_e32 v67, 0
	v_mov_b32_e32 v56, 0
	v_mov_b32_e32 v57, 0
	v_mov_b32_e32 v58, 0
	v_mov_b32_e32 v59, 0
	v_mov_b32_e32 v68, 0
	v_mov_b32_e32 v69, 0
	v_mov_b32_e32 v70, 0
	v_mov_b32_e32 v71, 0
	v_cndmask_b32_e32 v116, v117, v116, vcc
	v_cmp_ne_u32_e64 s[0:1], 0, v116
	v_cndmask_b32_e32 v117, v109, v108, vcc
	v_cmp_lt_u32_e64 s[2:3], v116, v117
	v_add_co_u32_e32 v118, vcc, 0x1000, v114
	s_nop 1
	v_addc_co_u32_e32 v119, vcc, 0, v115, vcc
	s_and_saveexec_b64 s[10:11], s[0:1]
	global_load_dwordx4 v[52:55], v[114:115], off offset:-2048
	global_load_dwordx4 v[64:67], v[114:115], off offset:-1024
	s_or_b64 exec, exec, s[10:11]
	s_and_saveexec_b64 s[10:11], s[2:3]
	global_load_dwordx4 v[56:59], v[118:119], off
	global_load_dwordx4 v[68:71], v[118:119], off offset:1024
	s_or_b64 exec, exec, s[10:11]
	s_lshl_b32 s2, s19, 7
	v_add_u32_e32 v120, 64, v113
	v_mad_i64_i32 v[114:115], s[0:1], v120, s15, v[102:103]
	v_lshl_add_u64 v[114:115], v[114:115], 0, v[98:99]
	global_load_dwordx4 v[72:75], v[114:115], off offset:1024
	global_load_dwordx4 v[84:87], v[114:115], off offset:2048
	v_and_b32_e32 v116, 0xfff, v120
	v_add_u32_e32 v117, 0xffffc040, v113
	v_cmp_gt_i32_e32 vcc, s16, v113
	v_mov_b32_e32 v76, 0
	v_mov_b32_e32 v77, 0
	v_mov_b32_e32 v78, 0
	v_mov_b32_e32 v79, 0
	v_mov_b32_e32 v88, 0
	v_mov_b32_e32 v89, 0
	v_mov_b32_e32 v90, 0
	v_mov_b32_e32 v91, 0
	v_mov_b32_e32 v80, 0
	v_mov_b32_e32 v81, 0
	v_mov_b32_e32 v82, 0
	v_mov_b32_e32 v83, 0
	v_mov_b32_e32 v92, 0
	v_mov_b32_e32 v93, 0
	v_mov_b32_e32 v94, 0
	v_mov_b32_e32 v95, 0
	v_cndmask_b32_e32 v116, v117, v116, vcc
	v_cmp_ne_u32_e64 s[0:1], 0, v116
	v_cndmask_b32_e32 v117, v109, v108, vcc
	v_cmp_lt_u32_e64 s[2:3], v116, v117
	v_add_co_u32_e32 v118, vcc, 0x1000, v114
	s_nop 1
	v_addc_co_u32_e32 v119, vcc, 0, v115, vcc
	s_and_saveexec_b64 s[10:11], s[0:1]
	global_load_dwordx4 v[76:79], v[114:115], off offset:-2048
	global_load_dwordx4 v[88:91], v[114:115], off offset:-1024
	s_or_b64 exec, exec, s[10:11]
	s_and_saveexec_b64 s[10:11], s[2:3]
	global_load_dwordx4 v[80:83], v[118:119], off
	global_load_dwordx4 v[92:95], v[118:119], off offset:1024
	s_or_b64 exec, exec, s[10:11]
	v_add_u32_e32 v116, s20, v104
	v_lshlrev_b32_e32 v120, 16, v116
	v_mov_b32_e32 v121, 0
	v_add_lshl_u32 v117, v116, s19, 7
	v_and_or_b32 v117, v117, s17, v105
	v_lshl_add_u64 v[120:121], s[60:61], 0, v[120:121]
	v_lshlrev_b32_e32 v122, 1, v117
	v_mov_b32_e32 v123, 0
	v_lshl_add_u64 v[236:237], v[120:121], 0, v[122:123]
	s_waitcnt vmcnt(18)
	v_lshlrev_b32_e32 v124, 16, v0
	v_lshlrev_b32_e32 v125, 16, v4
	v_lshlrev_b32_e32 v126, 16, v8
	v_lshlrev_b32_e32 v127, 16, v12
	v_lshlrev_b32_e32 v128, 16, v16
	v_lshlrev_b32_e32 v129, 16, v20
	v_mul_f32_e32 v124, v170, v124
	v_mul_f32_e32 v127, v202, v127
	v_fmac_f32_e32 v124, v178, v125
	v_fmac_f32_e32 v127, v210, v128
	v_fmac_f32_e32 v124, v186, v126
	v_fmac_f32_e32 v127, v218, v129
	v_add_f32_e32 v124, v194, v124
	v_add_f32_e32 v127, v226, v127
	v_mul_f32_e32 v124, v124, v127
	v_cvt_pk_bf16_f32 v130, v124, v124
	ds_write_b16 v110, v130
	v_and_b32_e32 v124, 0xffff0000, v0
	v_and_b32_e32 v125, 0xffff0000, v4
	v_and_b32_e32 v126, 0xffff0000, v8
	v_and_b32_e32 v127, 0xffff0000, v12
	v_and_b32_e32 v128, 0xffff0000, v16
	v_and_b32_e32 v129, 0xffff0000, v20
	v_mul_f32_e32 v124, v171, v124
	v_mul_f32_e32 v127, v203, v127
	v_fmac_f32_e32 v124, v179, v125
	v_fmac_f32_e32 v127, v211, v128
	v_fmac_f32_e32 v124, v187, v126
	v_fmac_f32_e32 v127, v219, v129
	v_add_f32_e32 v124, v195, v124
	v_add_f32_e32 v127, v227, v127
	v_mul_f32_e32 v124, v124, v127
	v_cvt_pk_bf16_f32 v131, v124, v124
	ds_write_b16 v110, v131 offset:272
	v_lshlrev_b32_e32 v124, 16, v1
	v_lshlrev_b32_e32 v125, 16, v5
	v_lshlrev_b32_e32 v126, 16, v9
	v_lshlrev_b32_e32 v127, 16, v13
	v_lshlrev_b32_e32 v128, 16, v17
	v_lshlrev_b32_e32 v129, 16, v21
	v_mul_f32_e32 v124, v172, v124
	v_mul_f32_e32 v127, v204, v127
	v_fmac_f32_e32 v124, v180, v125
	v_fmac_f32_e32 v127, v212, v128
	v_fmac_f32_e32 v124, v188, v126
	v_fmac_f32_e32 v127, v220, v129
	v_add_f32_e32 v124, v196, v124
	v_add_f32_e32 v127, v228, v127
	v_mul_f32_e32 v124, v124, v127
	v_cvt_pk_bf16_f32 v130, v124, v124
	ds_write_b16 v110, v130 offset:544
	v_and_b32_e32 v124, 0xffff0000, v1
	v_and_b32_e32 v125, 0xffff0000, v5
	v_and_b32_e32 v126, 0xffff0000, v9
	v_and_b32_e32 v127, 0xffff0000, v13
	v_and_b32_e32 v128, 0xffff0000, v17
	v_and_b32_e32 v129, 0xffff0000, v21
	v_mul_f32_e32 v124, v173, v124
	v_mul_f32_e32 v127, v205, v127
	v_fmac_f32_e32 v124, v181, v125
	v_fmac_f32_e32 v127, v213, v128
	v_fmac_f32_e32 v124, v189, v126
	v_fmac_f32_e32 v127, v221, v129
	v_add_f32_e32 v124, v197, v124
	v_add_f32_e32 v127, v229, v127
	v_mul_f32_e32 v124, v124, v127
	v_cvt_pk_bf16_f32 v131, v124, v124
	ds_write_b16 v110, v131 offset:816
	v_lshlrev_b32_e32 v124, 16, v2
	v_lshlrev_b32_e32 v125, 16, v6
; #define LAS __attribute__((address_space(3)))
; DI bf16 f2bf(float f) { return (bf16)(pk2(f, 0.f) & 0xffffu); }
; DI void p2b_unit(const Frame& F, int unit, const bf16* HY, bf16* UT, const float* cw, const float* cb) {
;     ...
; #pragma unroll
;       for (int j = 0; j < 2; ++j) { float x1[8], hv[8]; conv3_do(W1, xa[j], xb[j], xc[j], x1); conv3_do(WV, va[j], vb[j], vc[j], hv);
; #pragma unroll
;           for (int e = 0; e < 8; ++e) *(LAS bf16*)(T + (cc + e) * TR_ROW + (t0 + 64 * j) * 2) = f2bf(x1[e] * hv[e]); } }
;     __syncthreads();
	v_lshlrev_b32_e32 v126, 16, v10
	v_lshlrev_b32_e32 v127, 16, v14
	v_lshlrev_b32_e32 v128, 16, v18
	v_lshlrev_b32_e32 v129, 16, v22
	v_mul_f32_e32 v124, v174, v124
	v_mul_f32_e32 v127, v206, v127
	v_fmac_f32_e32 v124, v182, v125
	v_fmac_f32_e32 v127, v214, v128
	v_fmac_f32_e32 v124, v190, v126
	v_fmac_f32_e32 v127, v222, v129
	v_add_f32_e32 v124, v198, v124
	v_add_f32_e32 v127, v230, v127
	v_mul_f32_e32 v124, v124, v127
	v_cvt_pk_bf16_f32 v130, v124, v124
	ds_write_b16 v110, v130 offset:1088
	v_and_b32_e32 v124, 0xffff0000, v2
	v_and_b32_e32 v125, 0xffff0000, v6
	v_and_b32_e32 v126, 0xffff0000, v10
	v_and_b32_e32 v127, 0xffff0000, v14
	v_and_b32_e32 v128, 0xffff0000, v18
	v_and_b32_e32 v129, 0xffff0000, v22
	v_mul_f32_e32 v124, v175, v124
	v_mul_f32_e32 v127, v207, v127
	v_fmac_f32_e32 v124, v183, v125
	v_fmac_f32_e32 v127, v215, v128
	v_fmac_f32_e32 v124, v191, v126
	v_fmac_f32_e32 v127, v223, v129
	v_add_f32_e32 v124, v199, v124
	v_add_f32_e32 v127, v231, v127
	v_mul_f32_e32 v124, v124, v127
	v_cvt_pk_bf16_f32 v131, v124, v124
	ds_write_b16 v110, v131 offset:1360
	v_lshlrev_b32_e32 v124, 16, v3
	v_lshlrev_b32_e32 v125, 16, v7
	v_lshlrev_b32_e32 v126, 16, v11
	v_lshlrev_b32_e32 v127, 16, v15
	v_lshlrev_b32_e32 v128, 16, v19
	v_lshlrev_b32_e32 v129, 16, v23
	v_mul_f32_e32 v124, v176, v124
	v_mul_f32_e32 v127, v208, v127
	v_fmac_f32_e32 v124, v184, v125
	v_fmac_f32_e32 v127, v216, v128
	v_fmac_f32_e32 v124, v192, v126
	v_fmac_f32_e32 v127, v224, v129
	v_add_f32_e32 v124, v200, v124
	v_add_f32_e32 v127, v232, v127
	v_mul_f32_e32 v124, v124, v127
	v_cvt_pk_bf16_f32 v130, v124, v124
	ds_write_b16 v110, v130 offset:1632
	v_and_b32_e32 v124, 0xffff0000, v3
	v_and_b32_e32 v125, 0xffff0000, v7
	v_and_b32_e32 v126, 0xffff0000, v11
	v_and_b32_e32 v127, 0xffff0000, v15
	v_and_b32_e32 v128, 0xffff0000, v19
	v_and_b32_e32 v129, 0xffff0000, v23
	v_mul_f32_e32 v124, v177, v124
	v_mul_f32_e32 v127, v209, v127
	v_fmac_f32_e32 v124, v185, v125
	v_fmac_f32_e32 v127, v217, v128
	v_fmac_f32_e32 v124, v193, v126
	v_fmac_f32_e32 v127, v225, v129
	v_add_f32_e32 v124, v201, v124
	v_add_f32_e32 v127, v233, v127
	v_mul_f32_e32 v124, v124, v127
	v_cvt_pk_bf16_f32 v131, v124, v124
	ds_write_b16 v110, v131 offset:1904
	s_waitcnt vmcnt(12)
	v_lshlrev_b32_e32 v124, 16, v24
	v_lshlrev_b32_e32 v125, 16, v28
	v_lshlrev_b32_e32 v126, 16, v32
	v_lshlrev_b32_e32 v127, 16, v36
	v_lshlrev_b32_e32 v128, 16, v40
	v_lshlrev_b32_e32 v129, 16, v44
	v_mul_f32_e32 v124, v170, v124
	v_mul_f32_e32 v127, v202, v127
	v_fmac_f32_e32 v124, v178, v125
	v_fmac_f32_e32 v127, v210, v128
	v_fmac_f32_e32 v124, v186, v126
	v_fmac_f32_e32 v127, v218, v129
	v_add_f32_e32 v124, v194, v124
	v_add_f32_e32 v127, v226, v127
	v_mul_f32_e32 v124, v124, v127
	v_cvt_pk_bf16_f32 v130, v124, v124
	ds_write_b16 v110, v130 offset:128
	v_and_b32_e32 v124, 0xffff0000, v24
	v_and_b32_e32 v125, 0xffff0000, v28
	v_and_b32_e32 v126, 0xffff0000, v32
	v_and_b32_e32 v127, 0xffff0000, v36
	v_and_b32_e32 v128, 0xffff0000, v40
	v_and_b32_e32 v129, 0xffff0000, v44
	v_mul_f32_e32 v124, v171, v124
	v_mul_f32_e32 v127, v203, v127
	v_fmac_f32_e32 v124, v179, v125
	v_fmac_f32_e32 v127, v211, v128
	v_fmac_f32_e32 v124, v187, v126
	v_fmac_f32_e32 v127, v219, v129
	v_add_f32_e32 v124, v195, v124
	v_add_f32_e32 v127, v227, v127
	v_mul_f32_e32 v124, v124, v127
	v_cvt_pk_bf16_f32 v131, v124, v124
	ds_write_b16 v110, v131 offset:400
	v_lshlrev_b32_e32 v124, 16, v25
	v_lshlrev_b32_e32 v125, 16, v29
	v_lshlrev_b32_e32 v126, 16, v33
	v_lshlrev_b32_e32 v127, 16, v37
	v_lshlrev_b32_e32 v128, 16, v41
	v_lshlrev_b32_e32 v129, 16, v45
	v_mul_f32_e32 v124, v172, v124
	v_mul_f32_e32 v127, v204, v127
	v_fmac_f32_e32 v124, v180, v125
	v_fmac_f32_e32 v127, v212, v128
	v_fmac_f32_e32 v124, v188, v126
	v_fmac_f32_e32 v127, v220, v129
	v_add_f32_e32 v124, v196, v124
	v_add_f32_e32 v127, v228, v127
	v_mul_f32_e32 v124, v124, v127
	v_cvt_pk_bf16_f32 v130, v124, v124
	ds_write_b16 v110, v130 offset:672
	v_and_b32_e32 v124, 0xffff0000, v25
	v_and_b32_e32 v125, 0xffff0000, v29
	v_and_b32_e32 v126, 0xffff0000, v33
	v_and_b32_e32 v127, 0xffff0000, v37
	v_and_b32_e32 v128, 0xffff0000, v41
	v_and_b32_e32 v129, 0xffff0000, v45
	v_mul_f32_e32 v124, v173, v124
	v_mul_f32_e32 v127, v205, v127
	v_fmac_f32_e32 v124, v181, v125
	v_fmac_f32_e32 v127, v213, v128
	v_fmac_f32_e32 v124, v189, v126
	v_fmac_f32_e32 v127, v221, v129
	v_add_f32_e32 v124, v197, v124
	v_add_f32_e32 v127, v229, v127
	v_mul_f32_e32 v124, v124, v127
	v_cvt_pk_bf16_f32 v131, v124, v124
	ds_write_b16 v110, v131 offset:944
	v_lshlrev_b32_e32 v124, 16, v26
	v_lshlrev_b32_e32 v125, 16, v30
	v_lshlrev_b32_e32 v126, 16, v34
	v_lshlrev_b32_e32 v127, 16, v38
	v_lshlrev_b32_e32 v128, 16, v42
	v_lshlrev_b32_e32 v129, 16, v46
	v_mul_f32_e32 v124, v174, v124
	v_mul_f32_e32 v127, v206, v127
	v_fmac_f32_e32 v124, v182, v125
	v_fmac_f32_e32 v127, v214, v128
	v_fmac_f32_e32 v124, v190, v126
	v_fmac_f32_e32 v127, v222, v129
	v_add_f32_e32 v124, v198, v124
	v_add_f32_e32 v127, v230, v127
	v_mul_f32_e32 v124, v124, v127
	v_cvt_pk_bf16_f32 v130, v124, v124
	ds_write_b16 v110, v130 offset:1216
	v_and_b32_e32 v124, 0xffff0000, v26
	v_and_b32_e32 v125, 0xffff0000, v30
	v_and_b32_e32 v126, 0xffff0000, v34
	v_and_b32_e32 v127, 0xffff0000, v38
	v_and_b32_e32 v128, 0xffff0000, v42
	v_and_b32_e32 v129, 0xffff0000, v46
	v_mul_f32_e32 v124, v175, v124
	v_mul_f32_e32 v127, v207, v127
	v_fmac_f32_e32 v124, v183, v125
	v_fmac_f32_e32 v127, v215, v128
	v_fmac_f32_e32 v124, v191, v126
	v_fmac_f32_e32 v127, v223, v129
	v_add_f32_e32 v124, v199, v124
	v_add_f32_e32 v127, v231, v127
	v_mul_f32_e32 v124, v124, v127
	v_cvt_pk_bf16_f32 v131, v124, v124
	ds_write_b16 v110, v131 offset:1488
	v_lshlrev_b32_e32 v124, 16, v27
	v_lshlrev_b32_e32 v125, 16, v31
	v_lshlrev_b32_e32 v126, 16, v35
	v_lshlrev_b32_e32 v127, 16, v39
	v_lshlrev_b32_e32 v128, 16, v43
	v_lshlrev_b32_e32 v129, 16, v47
	v_mul_f32_e32 v124, v176, v124
	v_mul_f32_e32 v127, v208, v127
	v_fmac_f32_e32 v124, v184, v125
	v_fmac_f32_e32 v127, v216, v128
	v_fmac_f32_e32 v124, v192, v126
	v_fmac_f32_e32 v127, v224, v129
	v_add_f32_e32 v124, v200, v124
	v_add_f32_e32 v127, v232, v127
	v_mul_f32_e32 v124, v124, v127
	v_cvt_pk_bf16_f32 v130, v124, v124
	ds_write_b16 v110, v130 offset:1760
	v_and_b32_e32 v124, 0xffff0000, v27
	v_and_b32_e32 v125, 0xffff0000, v31
	v_and_b32_e32 v126, 0xffff0000, v35
	v_and_b32_e32 v127, 0xffff0000, v39
	v_and_b32_e32 v128, 0xffff0000, v43
	v_and_b32_e32 v129, 0xffff0000, v47
	v_mul_f32_e32 v124, v177, v124
	v_mul_f32_e32 v127, v209, v127
	v_fmac_f32_e32 v124, v185, v125
	v_fmac_f32_e32 v127, v217, v128
	v_fmac_f32_e32 v124, v193, v126
	v_fmac_f32_e32 v127, v225, v129
	v_add_f32_e32 v124, v201, v124
	v_add_f32_e32 v127, v233, v127
	v_mul_f32_e32 v124, v124, v127
	v_cvt_pk_bf16_f32 v131, v124, v124
	ds_write_b16 v110, v131 offset:2032
	s_waitcnt lgkmcnt(0)
	s_barrier
; #define LAS __attribute__((address_space(3)))
; DI bf16 f2bf(float f) { return (bf16)(pk2(f, 0.f) & 0xffffu); }
; DI int rot_t(int c, int t) { return (t + 128 * c) & (MTOK - 1); }
; DI void p2b_unit(const Frame& F, int unit, const bf16* HY, bf16* UT, const float* cw, const float* cb) {
;     ...
;     { const int t0 = F.tid >> 3, cc = (F.tid & 7) * 8, c0 = cgp * 64 + cc;
;       u32x4 xa[2], xb[2], xc[2], va[2], vb[2], vc[2];
; #pragma unroll
;       for (int j = 0; j < 2; ++j) { const int tok = tt * 128 + t0 + 64 * j; bool hp, hn; tok_edges(tok, hp, hn);
;           conv3_load(HY, tok, 512 + c0, hp, hn, xa[j], xb[j], xc[j]); conv3_load(HY, tok, 1024 + c0, hp, hn, va[j], vb[j], vc[j]); }
;       ConvW W1, WV; conv3_w(W1, cw, cb, 512 + c0); conv3_w(WV, cw, cb, 1024 + c0);
; #pragma unroll
;       for (int j = 0; j < 2; ++j) { float x1[8], hv[8]; conv3_do(W1, xa[j], xb[j], xc[j], x1); conv3_do(WV, va[j], vb[j], vc[j], hv);
; #pragma unroll
;           for (int e = 0; e < 8; ++e) *(LAS bf16*)(T + (cc + e) * TR_ROW + (t0 + 64 * j) * 2) = f2bf(x1[e] * hv[e]); } }
;     ...
;     { const int c = F.tid >> 3, cg = cgp * 64 + c;
; #pragma unroll
;       for (int j = 0; j < 2; ++j) { const int tch = (F.tid & 7) * 8 + 64 * j;
;           *(u32x4*)(UT + (size_t)cg * MTOK + rot_t(cg, tt * 128 + tch)) = *(const LAS u32x4*)(T + c * TR_ROW + tch * 2); } }
	ds_read_b128 v[132:135], v96
	ds_read_b128 v[136:139], v111
	s_waitcnt lgkmcnt(1)
	global_store_dwordx4 v[234:235], v[132:135], off
	s_waitcnt lgkmcnt(0)
	global_store_dwordx4 v[234:235], v[136:139], off offset:128
	s_add_i32 s18, s21, s89
	s_add_i32 s12, s22, s13
	s_cmpk_lt_i32 s18, 0x800
	s_cbranch_scc0 .Lp2b_lastB
	s_ashr_i32 s19, s18, 3
	s_and_b32 s20, s12, 0x1c0
	s_lshl_b32 s2, s19, 7
	v_or_b32_e32 v112, s20, v105
	v_or_b32_e32 v113, s2, v104
	v_mad_i64_i32 v[114:115], s[0:1], v113, s15, v[102:103]
	v_lshlrev_b32_e32 v98, 1, v112
	v_mov_b32_e32 v99, 0
	v_lshl_add_u64 v[114:115], v[114:115], 0, v[98:99]
	global_load_dwordx4 v[0:3], v[114:115], off offset:1024
	global_load_dwordx4 v[12:15], v[114:115], off offset:2048
	v_bitop3_b32 v116, s2, v108, v104 bitop3:0xc8
	v_add_u32_e32 v117, 0xffffc000, v113
	v_cmp_gt_i32_e32 vcc, s14, v113
	v_mov_b32_e32 v4, 0
	v_mov_b32_e32 v5, 0
	v_mov_b32_e32 v6, 0
	v_mov_b32_e32 v7, 0
	v_mov_b32_e32 v16, 0
	v_mov_b32_e32 v17, 0
	v_mov_b32_e32 v18, 0
	v_mov_b32_e32 v19, 0
	v_mov_b32_e32 v8, 0
	v_mov_b32_e32 v9, 0
	v_mov_b32_e32 v10, 0
	v_mov_b32_e32 v11, 0
	v_mov_b32_e32 v20, 0
	v_mov_b32_e32 v21, 0
	v_mov_b32_e32 v22, 0
	v_mov_b32_e32 v23, 0
	v_cndmask_b32_e32 v116, v117, v116, vcc
	v_cmp_ne_u32_e64 s[0:1], 0, v116
	v_cndmask_b32_e32 v117, v109, v108, vcc
	v_cmp_lt_u32_e64 s[2:3], v116, v117
	v_add_co_u32_e32 v118, vcc, 0x1000, v114
	s_nop 1
	v_addc_co_u32_e32 v119, vcc, 0, v115, vcc
	s_and_saveexec_b64 s[10:11], s[0:1]
	global_load_dwordx4 v[4:7], v[114:115], off offset:-2048
	global_load_dwordx4 v[16:19], v[114:115], off offset:-1024
	s_or_b64 exec, exec, s[10:11]
	s_and_saveexec_b64 s[10:11], s[2:3]
	global_load_dwordx4 v[8:11], v[118:119], off
	global_load_dwordx4 v[20:23], v[118:119], off offset:1024
	s_or_b64 exec, exec, s[10:11]
	s_lshl_b32 s2, s19, 7
	v_add_u32_e32 v120, 64, v113
	v_mad_i64_i32 v[114:115], s[0:1], v120, s15, v[102:103]
	v_lshl_add_u64 v[114:115], v[114:115], 0, v[98:99]
	global_load_dwordx4 v[24:27], v[114:115], off offset:1024
	global_load_dwordx4 v[36:39], v[114:115], off offset:2048
	v_and_b32_e32 v116, 0xfff, v120
	v_add_u32_e32 v117, 0xffffc040, v113
	v_cmp_gt_i32_e32 vcc, s16, v113
	v_mov_b32_e32 v28, 0
	v_mov_b32_e32 v29, 0
	v_mov_b32_e32 v30, 0
	v_mov_b32_e32 v31, 0
	v_mov_b32_e32 v40, 0
	v_mov_b32_e32 v41, 0
	v_mov_b32_e32 v42, 0
	v_mov_b32_e32 v43, 0
	v_mov_b32_e32 v32, 0
	v_mov_b32_e32 v33, 0
	v_mov_b32_e32 v34, 0
	v_mov_b32_e32 v35, 0
	v_mov_b32_e32 v44, 0
	v_mov_b32_e32 v45, 0
	v_mov_b32_e32 v46, 0
	v_mov_b32_e32 v47, 0
	v_cndmask_b32_e32 v116, v117, v116, vcc
	v_cmp_ne_u32_e64 s[0:1], 0, v116
	v_cndmask_b32_e32 v117, v109, v108, vcc
	v_cmp_lt_u32_e64 s[2:3], v116, v117
	v_add_co_u32_e32 v118, vcc, 0x1000, v114
	s_nop 1
	v_addc_co_u32_e32 v119, vcc, 0, v115, vcc
	s_and_saveexec_b64 s[10:11], s[0:1]
	global_load_dwordx4 v[28:31], v[114:115], off offset:-2048
	global_load_dwordx4 v[40:43], v[114:115], off offset:-1024
	s_or_b64 exec, exec, s[10:11]
	s_and_saveexec_b64 s[10:11], s[2:3]
	global_load_dwordx4 v[32:35], v[118:119], off
	global_load_dwordx4 v[44:47], v[118:119], off offset:1024
	s_or_b64 exec, exec, s[10:11]
	v_add_u32_e32 v116, s20, v104
	v_lshlrev_b32_e32 v120, 16, v116
	v_mov_b32_e32 v121, 0
	v_add_lshl_u32 v117, v116, s19, 7
	v_and_or_b32 v117, v117, s17, v105
	v_lshl_add_u64 v[120:121], s[60:61], 0, v[120:121]
	v_lshlrev_b32_e32 v122, 1, v117
	v_mov_b32_e32 v123, 0
	v_lshl_add_u64 v[234:235], v[120:121], 0, v[122:123]
	s_waitcnt vmcnt(18)
	v_lshlrev_b32_e32 v124, 16, v48
	v_lshlrev_b32_e32 v125, 16, v52
	v_lshlrev_b32_e32 v126, 16, v56
	v_lshlrev_b32_e32 v127, 16, v60
	v_lshlrev_b32_e32 v128, 16, v64
	v_lshlrev_b32_e32 v129, 16, v68
	v_mul_f32_e32 v124, v170, v124
	v_mul_f32_e32 v127, v202, v127
	v_fmac_f32_e32 v124, v178, v125
	v_fmac_f32_e32 v127, v210, v128
	v_fmac_f32_e32 v124, v186, v126
	v_fmac_f32_e32 v127, v218, v129
	v_add_f32_e32 v124, v194, v124
	v_add_f32_e32 v127, v226, v127
	v_mul_f32_e32 v124, v124, v127
	v_cvt_pk_bf16_f32 v130, v124, v124
	ds_write_b16 v110, v130 offset:18432
	v_and_b32_e32 v124, 0xffff0000, v48
	v_and_b32_e32 v125, 0xffff0000, v52
	v_and_b32_e32 v126, 0xffff0000, v56
	v_and_b32_e32 v127, 0xffff0000, v60
	v_and_b32_e32 v128, 0xffff0000, v64
	v_and_b32_e32 v129, 0xffff0000, v68
	v_mul_f32_e32 v124, v171, v124
	v_mul_f32_e32 v127, v203, v127
	v_fmac_f32_e32 v124, v179, v125
	v_fmac_f32_e32 v127, v211, v128
	v_fmac_f32_e32 v124, v187, v126
	v_fmac_f32_e32 v127, v219, v129
	v_add_f32_e32 v124, v195, v124
	v_add_f32_e32 v127, v227, v127
	v_mul_f32_e32 v124, v124, v127
	v_cvt_pk_bf16_f32 v131, v124, v124
	ds_write_b16 v110, v131 offset:18704
	v_lshlrev_b32_e32 v124, 16, v49
	v_lshlrev_b32_e32 v125, 16, v53
	v_lshlrev_b32_e32 v126, 16, v57
	v_lshlrev_b32_e32 v127, 16, v61
	v_lshlrev_b32_e32 v128, 16, v65
	v_lshlrev_b32_e32 v129, 16, v69
	v_mul_f32_e32 v124, v172, v124
	v_mul_f32_e32 v127, v204, v127
	v_fmac_f32_e32 v124, v180, v125
	v_fmac_f32_e32 v127, v212, v128
	v_fmac_f32_e32 v124, v188, v126
	v_fmac_f32_e32 v127, v220, v129
	v_add_f32_e32 v124, v196, v124
	v_add_f32_e32 v127, v228, v127
	v_mul_f32_e32 v124, v124, v127
	v_cvt_pk_bf16_f32 v130, v124, v124
	ds_write_b16 v110, v130 offset:18976
	v_and_b32_e32 v124, 0xffff0000, v49
	v_and_b32_e32 v125, 0xffff0000, v53
	v_and_b32_e32 v126, 0xffff0000, v57
	v_and_b32_e32 v127, 0xffff0000, v61
	v_and_b32_e32 v128, 0xffff0000, v65
	v_and_b32_e32 v129, 0xffff0000, v69
	v_mul_f32_e32 v124, v173, v124
	v_mul_f32_e32 v127, v205, v127
	v_fmac_f32_e32 v124, v181, v125
	v_fmac_f32_e32 v127, v213, v128
	v_fmac_f32_e32 v124, v189, v126
	v_fmac_f32_e32 v127, v221, v129
	v_add_f32_e32 v124, v197, v124
; #define LAS __attribute__((address_space(3)))
; DI bf16 f2bf(float f) { return (bf16)(pk2(f, 0.f) & 0xffffu); }
; DI void p2b_unit(const Frame& F, int unit, const bf16* HY, bf16* UT, const float* cw, const float* cb) {
;     ...
; #pragma unroll
;       for (int j = 0; j < 2; ++j) { float x1[8], hv[8]; conv3_do(W1, xa[j], xb[j], xc[j], x1); conv3_do(WV, va[j], vb[j], vc[j], hv);
; #pragma unroll
;           for (int e = 0; e < 8; ++e) *(LAS bf16*)(T + (cc + e) * TR_ROW + (t0 + 64 * j) * 2) = f2bf(x1[e] * hv[e]); } }
	v_add_f32_e32 v127, v229, v127
	v_mul_f32_e32 v124, v124, v127
	v_cvt_pk_bf16_f32 v131, v124, v124
	ds_write_b16 v110, v131 offset:19248
	v_lshlrev_b32_e32 v124, 16, v50
	v_lshlrev_b32_e32 v125, 16, v54
	v_lshlrev_b32_e32 v126, 16, v58
	v_lshlrev_b32_e32 v127, 16, v62
	v_lshlrev_b32_e32 v128, 16, v66
	v_lshlrev_b32_e32 v129, 16, v70
	v_mul_f32_e32 v124, v174, v124
	v_mul_f32_e32 v127, v206, v127
	v_fmac_f32_e32 v124, v182, v125
	v_fmac_f32_e32 v127, v214, v128
	v_fmac_f32_e32 v124, v190, v126
	v_fmac_f32_e32 v127, v222, v129
	v_add_f32_e32 v124, v198, v124
	v_add_f32_e32 v127, v230, v127
	v_mul_f32_e32 v124, v124, v127
	v_cvt_pk_bf16_f32 v130, v124, v124
	ds_write_b16 v110, v130 offset:19520
	v_and_b32_e32 v124, 0xffff0000, v50
	v_and_b32_e32 v125, 0xffff0000, v54
	v_and_b32_e32 v126, 0xffff0000, v58
	v_and_b32_e32 v127, 0xffff0000, v62
	v_and_b32_e32 v128, 0xffff0000, v66
	v_and_b32_e32 v129, 0xffff0000, v70
	v_mul_f32_e32 v124, v175, v124
	v_mul_f32_e32 v127, v207, v127
	v_fmac_f32_e32 v124, v183, v125
	v_fmac_f32_e32 v127, v215, v128
	v_fmac_f32_e32 v124, v191, v126
	v_fmac_f32_e32 v127, v223, v129
	v_add_f32_e32 v124, v199, v124
	v_add_f32_e32 v127, v231, v127
	v_mul_f32_e32 v124, v124, v127
	v_cvt_pk_bf16_f32 v131, v124, v124
	ds_write_b16 v110, v131 offset:19792
	v_lshlrev_b32_e32 v124, 16, v51
	v_lshlrev_b32_e32 v125, 16, v55
	v_lshlrev_b32_e32 v126, 16, v59
	v_lshlrev_b32_e32 v127, 16, v63
	v_lshlrev_b32_e32 v128, 16, v67
	v_lshlrev_b32_e32 v129, 16, v71
	v_mul_f32_e32 v124, v176, v124
	v_mul_f32_e32 v127, v208, v127
	v_fmac_f32_e32 v124, v184, v125
	v_fmac_f32_e32 v127, v216, v128
	v_fmac_f32_e32 v124, v192, v126
	v_fmac_f32_e32 v127, v224, v129
	v_add_f32_e32 v124, v200, v124
	v_add_f32_e32 v127, v232, v127
	v_mul_f32_e32 v124, v124, v127
	v_cvt_pk_bf16_f32 v130, v124, v124
	ds_write_b16 v110, v130 offset:20064
	v_and_b32_e32 v124, 0xffff0000, v51
	v_and_b32_e32 v125, 0xffff0000, v55
	v_and_b32_e32 v126, 0xffff0000, v59
	v_and_b32_e32 v127, 0xffff0000, v63
	v_and_b32_e32 v128, 0xffff0000, v67
	v_and_b32_e32 v129, 0xffff0000, v71
	v_mul_f32_e32 v124, v177, v124
	v_mul_f32_e32 v127, v209, v127
	v_fmac_f32_e32 v124, v185, v125
	v_fmac_f32_e32 v127, v217, v128
	v_fmac_f32_e32 v124, v193, v126
	v_fmac_f32_e32 v127, v225, v129
	v_add_f32_e32 v124, v201, v124
	v_add_f32_e32 v127, v233, v127
	v_mul_f32_e32 v124, v124, v127
	v_cvt_pk_bf16_f32 v131, v124, v124
	ds_write_b16 v110, v131 offset:20336
	s_waitcnt vmcnt(12)
	v_lshlrev_b32_e32 v124, 16, v72
	v_lshlrev_b32_e32 v125, 16, v76
	v_lshlrev_b32_e32 v126, 16, v80
	v_lshlrev_b32_e32 v127, 16, v84
	v_lshlrev_b32_e32 v128, 16, v88
	v_lshlrev_b32_e32 v129, 16, v92
	v_mul_f32_e32 v124, v170, v124
	v_mul_f32_e32 v127, v202, v127
	v_fmac_f32_e32 v124, v178, v125
	v_fmac_f32_e32 v127, v210, v128
	v_fmac_f32_e32 v124, v186, v126
	v_fmac_f32_e32 v127, v218, v129
	v_add_f32_e32 v124, v194, v124
	v_add_f32_e32 v127, v226, v127
	v_mul_f32_e32 v124, v124, v127
	v_cvt_pk_bf16_f32 v130, v124, v124
	ds_write_b16 v110, v130 offset:18560
	v_and_b32_e32 v124, 0xffff0000, v72
	v_and_b32_e32 v125, 0xffff0000, v76
	v_and_b32_e32 v126, 0xffff0000, v80
	v_and_b32_e32 v127, 0xffff0000, v84
	v_and_b32_e32 v128, 0xffff0000, v88
	v_and_b32_e32 v129, 0xffff0000, v92
	v_mul_f32_e32 v124, v171, v124
	v_mul_f32_e32 v127, v203, v127
	v_fmac_f32_e32 v124, v179, v125
	v_fmac_f32_e32 v127, v211, v128
	v_fmac_f32_e32 v124, v187, v126
	v_fmac_f32_e32 v127, v219, v129
	v_add_f32_e32 v124, v195, v124
	v_add_f32_e32 v127, v227, v127
	v_mul_f32_e32 v124, v124, v127
	v_cvt_pk_bf16_f32 v131, v124, v124
	ds_write_b16 v110, v131 offset:18832
	v_lshlrev_b32_e32 v124, 16, v73
	v_lshlrev_b32_e32 v125, 16, v77
	v_lshlrev_b32_e32 v126, 16, v81
	v_lshlrev_b32_e32 v127, 16, v85
	v_lshlrev_b32_e32 v128, 16, v89
	v_lshlrev_b32_e32 v129, 16, v93
	v_mul_f32_e32 v124, v172, v124
	v_mul_f32_e32 v127, v204, v127
	v_fmac_f32_e32 v124, v180, v125
	v_fmac_f32_e32 v127, v212, v128
	v_fmac_f32_e32 v124, v188, v126
	v_fmac_f32_e32 v127, v220, v129
	v_add_f32_e32 v124, v196, v124
	v_add_f32_e32 v127, v228, v127
	v_mul_f32_e32 v124, v124, v127
	v_cvt_pk_bf16_f32 v130, v124, v124
	ds_write_b16 v110, v130 offset:19104
	v_and_b32_e32 v124, 0xffff0000, v73
	v_and_b32_e32 v125, 0xffff0000, v77
	v_and_b32_e32 v126, 0xffff0000, v81
	v_and_b32_e32 v127, 0xffff0000, v85
	v_and_b32_e32 v128, 0xffff0000, v89
	v_and_b32_e32 v129, 0xffff0000, v93
	v_mul_f32_e32 v124, v173, v124
	v_mul_f32_e32 v127, v205, v127
	v_fmac_f32_e32 v124, v181, v125
	v_fmac_f32_e32 v127, v213, v128
	v_fmac_f32_e32 v124, v189, v126
	v_fmac_f32_e32 v127, v221, v129
	v_add_f32_e32 v124, v197, v124
	v_add_f32_e32 v127, v229, v127
	v_mul_f32_e32 v124, v124, v127
	v_cvt_pk_bf16_f32 v131, v124, v124
	ds_write_b16 v110, v131 offset:19376
	v_lshlrev_b32_e32 v124, 16, v74
	v_lshlrev_b32_e32 v125, 16, v78
	v_lshlrev_b32_e32 v126, 16, v82
	v_lshlrev_b32_e32 v127, 16, v86
	v_lshlrev_b32_e32 v128, 16, v90
	v_lshlrev_b32_e32 v129, 16, v94
	v_mul_f32_e32 v124, v174, v124
	v_mul_f32_e32 v127, v206, v127
	v_fmac_f32_e32 v124, v182, v125
	v_fmac_f32_e32 v127, v214, v128
	v_fmac_f32_e32 v124, v190, v126
	v_fmac_f32_e32 v127, v222, v129
	v_add_f32_e32 v124, v198, v124
	v_add_f32_e32 v127, v230, v127
	v_mul_f32_e32 v124, v124, v127
	v_cvt_pk_bf16_f32 v130, v124, v124
	ds_write_b16 v110, v130 offset:19648
	v_and_b32_e32 v124, 0xffff0000, v74
	v_and_b32_e32 v125, 0xffff0000, v78
	v_and_b32_e32 v126, 0xffff0000, v82
	v_and_b32_e32 v127, 0xffff0000, v86
	v_and_b32_e32 v128, 0xffff0000, v90
	v_and_b32_e32 v129, 0xffff0000, v94
	v_mul_f32_e32 v124, v175, v124
	v_mul_f32_e32 v127, v207, v127
	v_fmac_f32_e32 v124, v183, v125
; #define LAS __attribute__((address_space(3)))
; DI bf16 f2bf(float f) { return (bf16)(pk2(f, 0.f) & 0xffffu); }
; DI int rot_t(int c, int t) { return (t + 128 * c) & (MTOK - 1); }
; DI void p2b_unit(const Frame& F, int unit, const bf16* HY, bf16* UT, const float* cw, const float* cb) {
;     ...
; #pragma unroll
;       for (int j = 0; j < 2; ++j) { float x1[8], hv[8]; conv3_do(W1, xa[j], xb[j], xc[j], x1); conv3_do(WV, va[j], vb[j], vc[j], hv);
; #pragma unroll
;           for (int e = 0; e < 8; ++e) *(LAS bf16*)(T + (cc + e) * TR_ROW + (t0 + 64 * j) * 2) = f2bf(x1[e] * hv[e]); } }
;     __syncthreads();
;     { const int c = F.tid >> 3, cg = cgp * 64 + c;
; #pragma unroll
;       for (int j = 0; j < 2; ++j) { const int tch = (F.tid & 7) * 8 + 64 * j;
;           *(u32x4*)(UT + (size_t)cg * MTOK + rot_t(cg, tt * 128 + tch)) = *(const LAS u32x4*)(T + c * TR_ROW + tch * 2); } }
	v_fmac_f32_e32 v127, v215, v128
	v_fmac_f32_e32 v124, v191, v126
	v_fmac_f32_e32 v127, v223, v129
	v_add_f32_e32 v124, v199, v124
	v_add_f32_e32 v127, v231, v127
	v_mul_f32_e32 v124, v124, v127
	v_cvt_pk_bf16_f32 v131, v124, v124
	ds_write_b16 v110, v131 offset:19920
	v_lshlrev_b32_e32 v124, 16, v75
	v_lshlrev_b32_e32 v125, 16, v79
	v_lshlrev_b32_e32 v126, 16, v83
	v_lshlrev_b32_e32 v127, 16, v87
	v_lshlrev_b32_e32 v128, 16, v91
	v_lshlrev_b32_e32 v129, 16, v95
	v_mul_f32_e32 v124, v176, v124
	v_mul_f32_e32 v127, v208, v127
	v_fmac_f32_e32 v124, v184, v125
	v_fmac_f32_e32 v127, v216, v128
	v_fmac_f32_e32 v124, v192, v126
	v_fmac_f32_e32 v127, v224, v129
	v_add_f32_e32 v124, v200, v124
	v_add_f32_e32 v127, v232, v127
	v_mul_f32_e32 v124, v124, v127
	v_cvt_pk_bf16_f32 v130, v124, v124
	ds_write_b16 v110, v130 offset:20192
	v_and_b32_e32 v124, 0xffff0000, v75
	v_and_b32_e32 v125, 0xffff0000, v79
	v_and_b32_e32 v126, 0xffff0000, v83
	v_and_b32_e32 v127, 0xffff0000, v87
	v_and_b32_e32 v128, 0xffff0000, v91
	v_and_b32_e32 v129, 0xffff0000, v95
	v_mul_f32_e32 v124, v177, v124
	v_mul_f32_e32 v127, v209, v127
	v_fmac_f32_e32 v124, v185, v125
	v_fmac_f32_e32 v127, v217, v128
	v_fmac_f32_e32 v124, v193, v126
	v_fmac_f32_e32 v127, v225, v129
	v_add_f32_e32 v124, v201, v124
	v_add_f32_e32 v127, v233, v127
	v_mul_f32_e32 v124, v124, v127
	v_cvt_pk_bf16_f32 v131, v124, v124
	ds_write_b16 v110, v131 offset:20464
	s_waitcnt lgkmcnt(0)
	s_barrier
	ds_read_b128 v[132:135], v96 offset:18432
	ds_read_b128 v[136:139], v111 offset:18432
	s_waitcnt lgkmcnt(1)
	global_store_dwordx4 v[236:237], v[132:135], off
	s_waitcnt lgkmcnt(0)
	global_store_dwordx4 v[236:237], v[136:139], off offset:128
	s_branch .Lp2b_loop
.Lp2b_lastA:
	s_waitcnt vmcnt(6)
	v_lshlrev_b32_e32 v124, 16, v0
	v_lshlrev_b32_e32 v125, 16, v4
	v_lshlrev_b32_e32 v126, 16, v8
	v_lshlrev_b32_e32 v127, 16, v12
	v_lshlrev_b32_e32 v128, 16, v16
	v_lshlrev_b32_e32 v129, 16, v20
	v_mul_f32_e32 v124, v170, v124
	v_mul_f32_e32 v127, v202, v127
	v_fmac_f32_e32 v124, v178, v125
	v_fmac_f32_e32 v127, v210, v128
	v_fmac_f32_e32 v124, v186, v126
	v_fmac_f32_e32 v127, v218, v129
	v_add_f32_e32 v124, v194, v124
	v_add_f32_e32 v127, v226, v127
	v_mul_f32_e32 v124, v124, v127
	v_cvt_pk_bf16_f32 v130, v124, v124
	ds_write_b16 v110, v130
	v_and_b32_e32 v124, 0xffff0000, v0
	v_and_b32_e32 v125, 0xffff0000, v4
	v_and_b32_e32 v126, 0xffff0000, v8
	v_and_b32_e32 v127, 0xffff0000, v12
	v_and_b32_e32 v128, 0xffff0000, v16
	v_and_b32_e32 v129, 0xffff0000, v20
	v_mul_f32_e32 v124, v171, v124
	v_mul_f32_e32 v127, v203, v127
	v_fmac_f32_e32 v124, v179, v125
	v_fmac_f32_e32 v127, v211, v128
	v_fmac_f32_e32 v124, v187, v126
	v_fmac_f32_e32 v127, v219, v129
	v_add_f32_e32 v124, v195, v124
	v_add_f32_e32 v127, v227, v127
	v_mul_f32_e32 v124, v124, v127
	v_cvt_pk_bf16_f32 v131, v124, v124
	ds_write_b16 v110, v131 offset:272
	v_lshlrev_b32_e32 v124, 16, v1
	v_lshlrev_b32_e32 v125, 16, v5
	v_lshlrev_b32_e32 v126, 16, v9
	v_lshlrev_b32_e32 v127, 16, v13
	v_lshlrev_b32_e32 v128, 16, v17
	v_lshlrev_b32_e32 v129, 16, v21
	v_mul_f32_e32 v124, v172, v124
	v_mul_f32_e32 v127, v204, v127
	v_fmac_f32_e32 v124, v180, v125
	v_fmac_f32_e32 v127, v212, v128
	v_fmac_f32_e32 v124, v188, v126
	v_fmac_f32_e32 v127, v220, v129
	v_add_f32_e32 v124, v196, v124
	v_add_f32_e32 v127, v228, v127
	v_mul_f32_e32 v124, v124, v127
	v_cvt_pk_bf16_f32 v130, v124, v124
	ds_write_b16 v110, v130 offset:544
	v_and_b32_e32 v124, 0xffff0000, v1
	v_and_b32_e32 v125, 0xffff0000, v5
	v_and_b32_e32 v126, 0xffff0000, v9
	v_and_b32_e32 v127, 0xffff0000, v13
	v_and_b32_e32 v128, 0xffff0000, v17
	v_and_b32_e32 v129, 0xffff0000, v21
	v_mul_f32_e32 v124, v173, v124
	v_mul_f32_e32 v127, v205, v127
	v_fmac_f32_e32 v124, v181, v125
	v_fmac_f32_e32 v127, v213, v128
	v_fmac_f32_e32 v124, v189, v126
	v_fmac_f32_e32 v127, v221, v129
	v_add_f32_e32 v124, v197, v124
	v_add_f32_e32 v127, v229, v127
	v_mul_f32_e32 v124, v124, v127
	v_cvt_pk_bf16_f32 v131, v124, v124
	ds_write_b16 v110, v131 offset:816
	v_lshlrev_b32_e32 v124, 16, v2
	v_lshlrev_b32_e32 v125, 16, v6
	v_lshlrev_b32_e32 v126, 16, v10
	v_lshlrev_b32_e32 v127, 16, v14
	v_lshlrev_b32_e32 v128, 16, v18
	v_lshlrev_b32_e32 v129, 16, v22
	v_mul_f32_e32 v124, v174, v124
	v_mul_f32_e32 v127, v206, v127
	v_fmac_f32_e32 v124, v182, v125
	v_fmac_f32_e32 v127, v214, v128
	v_fmac_f32_e32 v124, v190, v126
	v_fmac_f32_e32 v127, v222, v129
	v_add_f32_e32 v124, v198, v124
	v_add_f32_e32 v127, v230, v127
	v_mul_f32_e32 v124, v124, v127
	v_cvt_pk_bf16_f32 v130, v124, v124
	ds_write_b16 v110, v130 offset:1088
	v_and_b32_e32 v124, 0xffff0000, v2
	v_and_b32_e32 v125, 0xffff0000, v6
	v_and_b32_e32 v126, 0xffff0000, v10
	v_and_b32_e32 v127, 0xffff0000, v14
	v_and_b32_e32 v128, 0xffff0000, v18
	v_and_b32_e32 v129, 0xffff0000, v22
	v_mul_f32_e32 v124, v175, v124
	v_mul_f32_e32 v127, v207, v127
	v_fmac_f32_e32 v124, v183, v125
	v_fmac_f32_e32 v127, v215, v128
	v_fmac_f32_e32 v124, v191, v126
	v_fmac_f32_e32 v127, v223, v129
	v_add_f32_e32 v124, v199, v124
	v_add_f32_e32 v127, v231, v127
	v_mul_f32_e32 v124, v124, v127
	v_cvt_pk_bf16_f32 v131, v124, v124
	ds_write_b16 v110, v131 offset:1360
	v_lshlrev_b32_e32 v124, 16, v3
	v_lshlrev_b32_e32 v125, 16, v7
	v_lshlrev_b32_e32 v126, 16, v11
	v_lshlrev_b32_e32 v127, 16, v15
	v_lshlrev_b32_e32 v128, 16, v19
	v_lshlrev_b32_e32 v129, 16, v23
	v_mul_f32_e32 v124, v176, v124
	v_mul_f32_e32 v127, v208, v127
	v_fmac_f32_e32 v124, v184, v125
	v_fmac_f32_e32 v127, v216, v128
	v_fmac_f32_e32 v124, v192, v126
	v_fmac_f32_e32 v127, v224, v129
	v_add_f32_e32 v124, v200, v124
	v_add_f32_e32 v127, v232, v127
	v_mul_f32_e32 v124, v124, v127
	v_cvt_pk_bf16_f32 v130, v124, v124
	ds_write_b16 v110, v130 offset:1632
	v_and_b32_e32 v124, 0xffff0000, v3
	v_and_b32_e32 v125, 0xffff0000, v7
	v_and_b32_e32 v126, 0xffff0000, v11
	v_and_b32_e32 v127, 0xffff0000, v15
	v_and_b32_e32 v128, 0xffff0000, v19
	v_and_b32_e32 v129, 0xffff0000, v23
	v_mul_f32_e32 v124, v177, v124
	v_mul_f32_e32 v127, v209, v127
	v_fmac_f32_e32 v124, v185, v125
	v_fmac_f32_e32 v127, v217, v128
	v_fmac_f32_e32 v124, v193, v126
	v_fmac_f32_e32 v127, v225, v129
	v_add_f32_e32 v124, v201, v124
	v_add_f32_e32 v127, v233, v127
	v_mul_f32_e32 v124, v124, v127
	v_cvt_pk_bf16_f32 v131, v124, v124
	ds_write_b16 v110, v131 offset:1904
	s_waitcnt vmcnt(0)
; #define LAS __attribute__((address_space(3)))
; DI bf16 f2bf(float f) { return (bf16)(pk2(f, 0.f) & 0xffffu); }
; DI int rot_t(int c, int t) { return (t + 128 * c) & (MTOK - 1); }
; DI void p2b_unit(const Frame& F, int unit, const bf16* HY, bf16* UT, const float* cw, const float* cb) {
;     ...
; #pragma unroll
;       for (int j = 0; j < 2; ++j) { float x1[8], hv[8]; conv3_do(W1, xa[j], xb[j], xc[j], x1); conv3_do(WV, va[j], vb[j], vc[j], hv);
; #pragma unroll
;           for (int e = 0; e < 8; ++e) *(LAS bf16*)(T + (cc + e) * TR_ROW + (t0 + 64 * j) * 2) = f2bf(x1[e] * hv[e]); } }
;     __syncthreads();
;     { const int c = F.tid >> 3, cg = cgp * 64 + c;
; #pragma unroll
;       for (int j = 0; j < 2; ++j) { const int tch = (F.tid & 7) * 8 + 64 * j;
;           *(u32x4*)(UT + (size_t)cg * MTOK + rot_t(cg, tt * 128 + tch)) = *(const LAS u32x4*)(T + c * TR_ROW + tch * 2); } }
	v_lshlrev_b32_e32 v124, 16, v24
	v_lshlrev_b32_e32 v125, 16, v28
	v_lshlrev_b32_e32 v126, 16, v32
	v_lshlrev_b32_e32 v127, 16, v36
	v_lshlrev_b32_e32 v128, 16, v40
	v_lshlrev_b32_e32 v129, 16, v44
	v_mul_f32_e32 v124, v170, v124
	v_mul_f32_e32 v127, v202, v127
	v_fmac_f32_e32 v124, v178, v125
	v_fmac_f32_e32 v127, v210, v128
	v_fmac_f32_e32 v124, v186, v126
	v_fmac_f32_e32 v127, v218, v129
	v_add_f32_e32 v124, v194, v124
	v_add_f32_e32 v127, v226, v127
	v_mul_f32_e32 v124, v124, v127
	v_cvt_pk_bf16_f32 v130, v124, v124
	ds_write_b16 v110, v130 offset:128
	v_and_b32_e32 v124, 0xffff0000, v24
	v_and_b32_e32 v125, 0xffff0000, v28
	v_and_b32_e32 v126, 0xffff0000, v32
	v_and_b32_e32 v127, 0xffff0000, v36
	v_and_b32_e32 v128, 0xffff0000, v40
	v_and_b32_e32 v129, 0xffff0000, v44
	v_mul_f32_e32 v124, v171, v124
	v_mul_f32_e32 v127, v203, v127
	v_fmac_f32_e32 v124, v179, v125
	v_fmac_f32_e32 v127, v211, v128
	v_fmac_f32_e32 v124, v187, v126
	v_fmac_f32_e32 v127, v219, v129
	v_add_f32_e32 v124, v195, v124
	v_add_f32_e32 v127, v227, v127
	v_mul_f32_e32 v124, v124, v127
	v_cvt_pk_bf16_f32 v131, v124, v124
	ds_write_b16 v110, v131 offset:400
	v_lshlrev_b32_e32 v124, 16, v25
	v_lshlrev_b32_e32 v125, 16, v29
	v_lshlrev_b32_e32 v126, 16, v33
	v_lshlrev_b32_e32 v127, 16, v37
	v_lshlrev_b32_e32 v128, 16, v41
	v_lshlrev_b32_e32 v129, 16, v45
	v_mul_f32_e32 v124, v172, v124
	v_mul_f32_e32 v127, v204, v127
	v_fmac_f32_e32 v124, v180, v125
	v_fmac_f32_e32 v127, v212, v128
	v_fmac_f32_e32 v124, v188, v126
	v_fmac_f32_e32 v127, v220, v129
	v_add_f32_e32 v124, v196, v124
	v_add_f32_e32 v127, v228, v127
	v_mul_f32_e32 v124, v124, v127
	v_cvt_pk_bf16_f32 v130, v124, v124
	ds_write_b16 v110, v130 offset:672
	v_and_b32_e32 v124, 0xffff0000, v25
	v_and_b32_e32 v125, 0xffff0000, v29
	v_and_b32_e32 v126, 0xffff0000, v33
	v_and_b32_e32 v127, 0xffff0000, v37
	v_and_b32_e32 v128, 0xffff0000, v41
	v_and_b32_e32 v129, 0xffff0000, v45
	v_mul_f32_e32 v124, v173, v124
	v_mul_f32_e32 v127, v205, v127
	v_fmac_f32_e32 v124, v181, v125
	v_fmac_f32_e32 v127, v213, v128
	v_fmac_f32_e32 v124, v189, v126
	v_fmac_f32_e32 v127, v221, v129
	v_add_f32_e32 v124, v197, v124
	v_add_f32_e32 v127, v229, v127
	v_mul_f32_e32 v124, v124, v127
	v_cvt_pk_bf16_f32 v131, v124, v124
	ds_write_b16 v110, v131 offset:944
	v_lshlrev_b32_e32 v124, 16, v26
	v_lshlrev_b32_e32 v125, 16, v30
	v_lshlrev_b32_e32 v126, 16, v34
	v_lshlrev_b32_e32 v127, 16, v38
	v_lshlrev_b32_e32 v128, 16, v42
	v_lshlrev_b32_e32 v129, 16, v46
	v_mul_f32_e32 v124, v174, v124
	v_mul_f32_e32 v127, v206, v127
	v_fmac_f32_e32 v124, v182, v125
	v_fmac_f32_e32 v127, v214, v128
	v_fmac_f32_e32 v124, v190, v126
	v_fmac_f32_e32 v127, v222, v129
	v_add_f32_e32 v124, v198, v124
	v_add_f32_e32 v127, v230, v127
	v_mul_f32_e32 v124, v124, v127
	v_cvt_pk_bf16_f32 v130, v124, v124
	ds_write_b16 v110, v130 offset:1216
	v_and_b32_e32 v124, 0xffff0000, v26
	v_and_b32_e32 v125, 0xffff0000, v30
	v_and_b32_e32 v126, 0xffff0000, v34
	v_and_b32_e32 v127, 0xffff0000, v38
	v_and_b32_e32 v128, 0xffff0000, v42
	v_and_b32_e32 v129, 0xffff0000, v46
	v_mul_f32_e32 v124, v175, v124
	v_mul_f32_e32 v127, v207, v127
	v_fmac_f32_e32 v124, v183, v125
	v_fmac_f32_e32 v127, v215, v128
	v_fmac_f32_e32 v124, v191, v126
	v_fmac_f32_e32 v127, v223, v129
	v_add_f32_e32 v124, v199, v124
	v_add_f32_e32 v127, v231, v127
	v_mul_f32_e32 v124, v124, v127
	v_cvt_pk_bf16_f32 v131, v124, v124
	ds_write_b16 v110, v131 offset:1488
	v_lshlrev_b32_e32 v124, 16, v27
	v_lshlrev_b32_e32 v125, 16, v31
	v_lshlrev_b32_e32 v126, 16, v35
	v_lshlrev_b32_e32 v127, 16, v39
	v_lshlrev_b32_e32 v128, 16, v43
	v_lshlrev_b32_e32 v129, 16, v47
	v_mul_f32_e32 v124, v176, v124
	v_mul_f32_e32 v127, v208, v127
	v_fmac_f32_e32 v124, v184, v125
	v_fmac_f32_e32 v127, v216, v128
	v_fmac_f32_e32 v124, v192, v126
	v_fmac_f32_e32 v127, v224, v129
	v_add_f32_e32 v124, v200, v124
	v_add_f32_e32 v127, v232, v127
	v_mul_f32_e32 v124, v124, v127
	v_cvt_pk_bf16_f32 v130, v124, v124
	ds_write_b16 v110, v130 offset:1760
	v_and_b32_e32 v124, 0xffff0000, v27
	v_and_b32_e32 v125, 0xffff0000, v31
	v_and_b32_e32 v126, 0xffff0000, v35
	v_and_b32_e32 v127, 0xffff0000, v39
	v_and_b32_e32 v128, 0xffff0000, v43
	v_and_b32_e32 v129, 0xffff0000, v47
	v_mul_f32_e32 v124, v177, v124
	v_mul_f32_e32 v127, v209, v127
	v_fmac_f32_e32 v124, v185, v125
	v_fmac_f32_e32 v127, v217, v128
	v_fmac_f32_e32 v124, v193, v126
	v_fmac_f32_e32 v127, v225, v129
	v_add_f32_e32 v124, v201, v124
	v_add_f32_e32 v127, v233, v127
	v_mul_f32_e32 v124, v124, v127
	v_cvt_pk_bf16_f32 v131, v124, v124
	ds_write_b16 v110, v131 offset:2032
	s_waitcnt lgkmcnt(0)
	s_barrier
	ds_read_b128 v[132:135], v96
	ds_read_b128 v[136:139], v111
	s_waitcnt lgkmcnt(1)
	global_store_dwordx4 v[234:235], v[132:135], off
	s_waitcnt lgkmcnt(0)
	global_store_dwordx4 v[234:235], v[136:139], off offset:128
	s_branch .Lp2b_end
; #define LAS __attribute__((address_space(3)))
; DI bf16 f2bf(float f) { return (bf16)(pk2(f, 0.f) & 0xffffu); }
; DI void p2b_unit(const Frame& F, int unit, const bf16* HY, bf16* UT, const float* cw, const float* cb) {
;     ...
; #pragma unroll
;       for (int j = 0; j < 2; ++j) { float x1[8], hv[8]; conv3_do(W1, xa[j], xb[j], xc[j], x1); conv3_do(WV, va[j], vb[j], vc[j], hv);
; #pragma unroll
;           for (int e = 0; e < 8; ++e) *(LAS bf16*)(T + (cc + e) * TR_ROW + (t0 + 64 * j) * 2) = f2bf(x1[e] * hv[e]); } }
.Lp2b_lastB:
	s_waitcnt vmcnt(6)
	v_lshlrev_b32_e32 v124, 16, v48
	v_lshlrev_b32_e32 v125, 16, v52
	v_lshlrev_b32_e32 v126, 16, v56
	v_lshlrev_b32_e32 v127, 16, v60
	v_lshlrev_b32_e32 v128, 16, v64
	v_lshlrev_b32_e32 v129, 16, v68
	v_mul_f32_e32 v124, v170, v124
	v_mul_f32_e32 v127, v202, v127
	v_fmac_f32_e32 v124, v178, v125
	v_fmac_f32_e32 v127, v210, v128
	v_fmac_f32_e32 v124, v186, v126
	v_fmac_f32_e32 v127, v218, v129
	v_add_f32_e32 v124, v194, v124
	v_add_f32_e32 v127, v226, v127
	v_mul_f32_e32 v124, v124, v127
	v_cvt_pk_bf16_f32 v130, v124, v124
	ds_write_b16 v110, v130 offset:18432
	v_and_b32_e32 v124, 0xffff0000, v48
	v_and_b32_e32 v125, 0xffff0000, v52
	v_and_b32_e32 v126, 0xffff0000, v56
	v_and_b32_e32 v127, 0xffff0000, v60
	v_and_b32_e32 v128, 0xffff0000, v64
	v_and_b32_e32 v129, 0xffff0000, v68
	v_mul_f32_e32 v124, v171, v124
	v_mul_f32_e32 v127, v203, v127
	v_fmac_f32_e32 v124, v179, v125
	v_fmac_f32_e32 v127, v211, v128
	v_fmac_f32_e32 v124, v187, v126
	v_fmac_f32_e32 v127, v219, v129
	v_add_f32_e32 v124, v195, v124
	v_add_f32_e32 v127, v227, v127
	v_mul_f32_e32 v124, v124, v127
	v_cvt_pk_bf16_f32 v131, v124, v124
	ds_write_b16 v110, v131 offset:18704
	v_lshlrev_b32_e32 v124, 16, v49
	v_lshlrev_b32_e32 v125, 16, v53
	v_lshlrev_b32_e32 v126, 16, v57
	v_lshlrev_b32_e32 v127, 16, v61
	v_lshlrev_b32_e32 v128, 16, v65
	v_lshlrev_b32_e32 v129, 16, v69
	v_mul_f32_e32 v124, v172, v124
	v_mul_f32_e32 v127, v204, v127
	v_fmac_f32_e32 v124, v180, v125
	v_fmac_f32_e32 v127, v212, v128
	v_fmac_f32_e32 v124, v188, v126
	v_fmac_f32_e32 v127, v220, v129
	v_add_f32_e32 v124, v196, v124
	v_add_f32_e32 v127, v228, v127
	v_mul_f32_e32 v124, v124, v127
	v_cvt_pk_bf16_f32 v130, v124, v124
	ds_write_b16 v110, v130 offset:18976
	v_and_b32_e32 v124, 0xffff0000, v49
	v_and_b32_e32 v125, 0xffff0000, v53
	v_and_b32_e32 v126, 0xffff0000, v57
	v_and_b32_e32 v127, 0xffff0000, v61
	v_and_b32_e32 v128, 0xffff0000, v65
	v_and_b32_e32 v129, 0xffff0000, v69
	v_mul_f32_e32 v124, v173, v124
	v_mul_f32_e32 v127, v205, v127
	v_fmac_f32_e32 v124, v181, v125
	v_fmac_f32_e32 v127, v213, v128
	v_fmac_f32_e32 v124, v189, v126
	v_fmac_f32_e32 v127, v221, v129
	v_add_f32_e32 v124, v197, v124
	v_add_f32_e32 v127, v229, v127
	v_mul_f32_e32 v124, v124, v127
	v_cvt_pk_bf16_f32 v131, v124, v124
	ds_write_b16 v110, v131 offset:19248
	v_lshlrev_b32_e32 v124, 16, v50
	v_lshlrev_b32_e32 v125, 16, v54
	v_lshlrev_b32_e32 v126, 16, v58
	v_lshlrev_b32_e32 v127, 16, v62
	v_lshlrev_b32_e32 v128, 16, v66
	v_lshlrev_b32_e32 v129, 16, v70
	v_mul_f32_e32 v124, v174, v124
	v_mul_f32_e32 v127, v206, v127
	v_fmac_f32_e32 v124, v182, v125
	v_fmac_f32_e32 v127, v214, v128
	v_fmac_f32_e32 v124, v190, v126
	v_fmac_f32_e32 v127, v222, v129
	v_add_f32_e32 v124, v198, v124
	v_add_f32_e32 v127, v230, v127
	v_mul_f32_e32 v124, v124, v127
	v_cvt_pk_bf16_f32 v130, v124, v124
	ds_write_b16 v110, v130 offset:19520
	v_and_b32_e32 v124, 0xffff0000, v50
	v_and_b32_e32 v125, 0xffff0000, v54
	v_and_b32_e32 v126, 0xffff0000, v58
	v_and_b32_e32 v127, 0xffff0000, v62
	v_and_b32_e32 v128, 0xffff0000, v66
	v_and_b32_e32 v129, 0xffff0000, v70
	v_mul_f32_e32 v124, v175, v124
	v_mul_f32_e32 v127, v207, v127
	v_fmac_f32_e32 v124, v183, v125
	v_fmac_f32_e32 v127, v215, v128
	v_fmac_f32_e32 v124, v191, v126
	v_fmac_f32_e32 v127, v223, v129
	v_add_f32_e32 v124, v199, v124
	v_add_f32_e32 v127, v231, v127
	v_mul_f32_e32 v124, v124, v127
	v_cvt_pk_bf16_f32 v131, v124, v124
	ds_write_b16 v110, v131 offset:19792
	v_lshlrev_b32_e32 v124, 16, v51
	v_lshlrev_b32_e32 v125, 16, v55
	v_lshlrev_b32_e32 v126, 16, v59
	v_lshlrev_b32_e32 v127, 16, v63
	v_lshlrev_b32_e32 v128, 16, v67
	v_lshlrev_b32_e32 v129, 16, v71
	v_mul_f32_e32 v124, v176, v124
	v_mul_f32_e32 v127, v208, v127
	v_fmac_f32_e32 v124, v184, v125
	v_fmac_f32_e32 v127, v216, v128
	v_fmac_f32_e32 v124, v192, v126
	v_fmac_f32_e32 v127, v224, v129
	v_add_f32_e32 v124, v200, v124
	v_add_f32_e32 v127, v232, v127
	v_mul_f32_e32 v124, v124, v127
	v_cvt_pk_bf16_f32 v130, v124, v124
	ds_write_b16 v110, v130 offset:20064
	v_and_b32_e32 v124, 0xffff0000, v51
	v_and_b32_e32 v125, 0xffff0000, v55
	v_and_b32_e32 v126, 0xffff0000, v59
	v_and_b32_e32 v127, 0xffff0000, v63
	v_and_b32_e32 v128, 0xffff0000, v67
	v_and_b32_e32 v129, 0xffff0000, v71
	v_mul_f32_e32 v124, v177, v124
	v_mul_f32_e32 v127, v209, v127
	v_fmac_f32_e32 v124, v185, v125
	v_fmac_f32_e32 v127, v217, v128
	v_fmac_f32_e32 v124, v193, v126
	v_fmac_f32_e32 v127, v225, v129
	v_add_f32_e32 v124, v201, v124
	v_add_f32_e32 v127, v233, v127
	v_mul_f32_e32 v124, v124, v127
	v_cvt_pk_bf16_f32 v131, v124, v124
	ds_write_b16 v110, v131 offset:20336
	s_waitcnt vmcnt(0)
; #define LAS __attribute__((address_space(3)))
; DI bf16 f2bf(float f) { return (bf16)(pk2(f, 0.f) & 0xffffu); }
; DI int rot_t(int c, int t) { return (t + 128 * c) & (MTOK - 1); }
; DI void p2b_unit(const Frame& F, int unit, const bf16* HY, bf16* UT, const float* cw, const float* cb) {
;     ...
; #pragma unroll
;       for (int j = 0; j < 2; ++j) { float x1[8], hv[8]; conv3_do(W1, xa[j], xb[j], xc[j], x1); conv3_do(WV, va[j], vb[j], vc[j], hv);
; #pragma unroll
;           for (int e = 0; e < 8; ++e) *(LAS bf16*)(T + (cc + e) * TR_ROW + (t0 + 64 * j) * 2) = f2bf(x1[e] * hv[e]); } }
;     __syncthreads();
;     { const int c = F.tid >> 3, cg = cgp * 64 + c;
; #pragma unroll
;       for (int j = 0; j < 2; ++j) { const int tch = (F.tid & 7) * 8 + 64 * j;
;           *(u32x4*)(UT + (size_t)cg * MTOK + rot_t(cg, tt * 128 + tch)) = *(const LAS u32x4*)(T + c * TR_ROW + tch * 2); } }
;     __syncthreads();
	v_lshlrev_b32_e32 v124, 16, v72
	v_lshlrev_b32_e32 v125, 16, v76
	v_lshlrev_b32_e32 v126, 16, v80
	v_lshlrev_b32_e32 v127, 16, v84
	v_lshlrev_b32_e32 v128, 16, v88
	v_lshlrev_b32_e32 v129, 16, v92
	v_mul_f32_e32 v124, v170, v124
	v_mul_f32_e32 v127, v202, v127
	v_fmac_f32_e32 v124, v178, v125
	v_fmac_f32_e32 v127, v210, v128
	v_fmac_f32_e32 v124, v186, v126
	v_fmac_f32_e32 v127, v218, v129
	v_add_f32_e32 v124, v194, v124
	v_add_f32_e32 v127, v226, v127
	v_mul_f32_e32 v124, v124, v127
	v_cvt_pk_bf16_f32 v130, v124, v124
	ds_write_b16 v110, v130 offset:18560
	v_and_b32_e32 v124, 0xffff0000, v72
	v_and_b32_e32 v125, 0xffff0000, v76
	v_and_b32_e32 v126, 0xffff0000, v80
	v_and_b32_e32 v127, 0xffff0000, v84
	v_and_b32_e32 v128, 0xffff0000, v88
	v_and_b32_e32 v129, 0xffff0000, v92
	v_mul_f32_e32 v124, v171, v124
	v_mul_f32_e32 v127, v203, v127
	v_fmac_f32_e32 v124, v179, v125
	v_fmac_f32_e32 v127, v211, v128
	v_fmac_f32_e32 v124, v187, v126
	v_fmac_f32_e32 v127, v219, v129
	v_add_f32_e32 v124, v195, v124
	v_add_f32_e32 v127, v227, v127
	v_mul_f32_e32 v124, v124, v127
	v_cvt_pk_bf16_f32 v131, v124, v124
	ds_write_b16 v110, v131 offset:18832
	v_lshlrev_b32_e32 v124, 16, v73
	v_lshlrev_b32_e32 v125, 16, v77
	v_lshlrev_b32_e32 v126, 16, v81
	v_lshlrev_b32_e32 v127, 16, v85
	v_lshlrev_b32_e32 v128, 16, v89
	v_lshlrev_b32_e32 v129, 16, v93
	v_mul_f32_e32 v124, v172, v124
	v_mul_f32_e32 v127, v204, v127
	v_fmac_f32_e32 v124, v180, v125
	v_fmac_f32_e32 v127, v212, v128
	v_fmac_f32_e32 v124, v188, v126
	v_fmac_f32_e32 v127, v220, v129
	v_add_f32_e32 v124, v196, v124
	v_add_f32_e32 v127, v228, v127
	v_mul_f32_e32 v124, v124, v127
	v_cvt_pk_bf16_f32 v130, v124, v124
	ds_write_b16 v110, v130 offset:19104
	v_and_b32_e32 v124, 0xffff0000, v73
	v_and_b32_e32 v125, 0xffff0000, v77
	v_and_b32_e32 v126, 0xffff0000, v81
	v_and_b32_e32 v127, 0xffff0000, v85
	v_and_b32_e32 v128, 0xffff0000, v89
	v_and_b32_e32 v129, 0xffff0000, v93
	v_mul_f32_e32 v124, v173, v124
	v_mul_f32_e32 v127, v205, v127
	v_fmac_f32_e32 v124, v181, v125
	v_fmac_f32_e32 v127, v213, v128
	v_fmac_f32_e32 v124, v189, v126
	v_fmac_f32_e32 v127, v221, v129
	v_add_f32_e32 v124, v197, v124
	v_add_f32_e32 v127, v229, v127
	v_mul_f32_e32 v124, v124, v127
	v_cvt_pk_bf16_f32 v131, v124, v124
	ds_write_b16 v110, v131 offset:19376
	v_lshlrev_b32_e32 v124, 16, v74
	v_lshlrev_b32_e32 v125, 16, v78
	v_lshlrev_b32_e32 v126, 16, v82
	v_lshlrev_b32_e32 v127, 16, v86
	v_lshlrev_b32_e32 v128, 16, v90
	v_lshlrev_b32_e32 v129, 16, v94
	v_mul_f32_e32 v124, v174, v124
	v_mul_f32_e32 v127, v206, v127
	v_fmac_f32_e32 v124, v182, v125
	v_fmac_f32_e32 v127, v214, v128
	v_fmac_f32_e32 v124, v190, v126
	v_fmac_f32_e32 v127, v222, v129
	v_add_f32_e32 v124, v198, v124
	v_add_f32_e32 v127, v230, v127
	v_mul_f32_e32 v124, v124, v127
	v_cvt_pk_bf16_f32 v130, v124, v124
	ds_write_b16 v110, v130 offset:19648
	v_and_b32_e32 v124, 0xffff0000, v74
	v_and_b32_e32 v125, 0xffff0000, v78
	v_and_b32_e32 v126, 0xffff0000, v82
	v_and_b32_e32 v127, 0xffff0000, v86
	v_and_b32_e32 v128, 0xffff0000, v90
	v_and_b32_e32 v129, 0xffff0000, v94
	v_mul_f32_e32 v124, v175, v124
	v_mul_f32_e32 v127, v207, v127
	v_fmac_f32_e32 v124, v183, v125
	v_fmac_f32_e32 v127, v215, v128
	v_fmac_f32_e32 v124, v191, v126
	v_fmac_f32_e32 v127, v223, v129
	v_add_f32_e32 v124, v199, v124
	v_add_f32_e32 v127, v231, v127
	v_mul_f32_e32 v124, v124, v127
	v_cvt_pk_bf16_f32 v131, v124, v124
	ds_write_b16 v110, v131 offset:19920
	v_lshlrev_b32_e32 v124, 16, v75
	v_lshlrev_b32_e32 v125, 16, v79
	v_lshlrev_b32_e32 v126, 16, v83
	v_lshlrev_b32_e32 v127, 16, v87
	v_lshlrev_b32_e32 v128, 16, v91
	v_lshlrev_b32_e32 v129, 16, v95
	v_mul_f32_e32 v124, v176, v124
	v_mul_f32_e32 v127, v208, v127
	v_fmac_f32_e32 v124, v184, v125
	v_fmac_f32_e32 v127, v216, v128
	v_fmac_f32_e32 v124, v192, v126
	v_fmac_f32_e32 v127, v224, v129
	v_add_f32_e32 v124, v200, v124
	v_add_f32_e32 v127, v232, v127
	v_mul_f32_e32 v124, v124, v127
	v_cvt_pk_bf16_f32 v130, v124, v124
	ds_write_b16 v110, v130 offset:20192
	v_and_b32_e32 v124, 0xffff0000, v75
	v_and_b32_e32 v125, 0xffff0000, v79
	v_and_b32_e32 v126, 0xffff0000, v83
	v_and_b32_e32 v127, 0xffff0000, v87
	v_and_b32_e32 v128, 0xffff0000, v91
	v_and_b32_e32 v129, 0xffff0000, v95
	v_mul_f32_e32 v124, v177, v124
	v_mul_f32_e32 v127, v209, v127
	v_fmac_f32_e32 v124, v185, v125
	v_fmac_f32_e32 v127, v217, v128
	v_fmac_f32_e32 v124, v193, v126
	v_fmac_f32_e32 v127, v225, v129
	v_add_f32_e32 v124, v201, v124
	v_add_f32_e32 v127, v233, v127
	v_mul_f32_e32 v124, v124, v127
	v_cvt_pk_bf16_f32 v131, v124, v124
	ds_write_b16 v110, v131 offset:20464
	s_waitcnt lgkmcnt(0)
	s_barrier
	ds_read_b128 v[132:135], v96 offset:18432
	ds_read_b128 v[136:139], v111 offset:18432
	s_waitcnt lgkmcnt(1)
	global_store_dwordx4 v[236:237], v[132:135], off
	s_waitcnt lgkmcnt(0)
	global_store_dwordx4 v[236:237], v[136:139], off offset:128
.Lp2b_end:
	s_barrier
	s_branch .LBB0_699
	s_nop 0
	s_nop 0
	s_nop 0
	s_nop 0
	s_nop 0
	s_nop 0
	s_nop 0
	s_nop 0
	s_nop 0
	s_branch .LBB0_683
